# in-proj tile order WGM 2->4 as well
# baseline (speedup 1.0000x reference)
;     __host__ __device__ bool next(int i, Unit& u) const {
;         const long L = (long)i * G + c; if (L >= nwg) return false;
;         int wgid = (int)L; { const int q = nwg / NXCD, r = nwg % NXCD, xcd = wgid % NXCD, off = wgid / NXCD; wgid = (xcd < r ? xcd * (q + 1) : r * (q + 1) + (xcd - r) * q) + off; }
;         const int nig = WGM * nN, gid = wgid / nig, fm = gid * WGM, gsz = (nM - fm) < WGM ? (nM - fm) : WGM;
;         u.pm = fm + ((wgid % nig) % gsz); u.pn = (wgid % nig) / gsz; return true;
;     }
; __global__ void __launch_bounds__(512, 2) fwd_kernel(Args a_unused) {
;     ...
;         if (sp == 0 && (PHM & 2)) {
;             pg8::Gemm g{XB, (const bf16_t*)(ws + WS_WIN + l * SZ_WIN), SEQ, NINP, DM, DM}; pg8::StaticOrder S; S.init(SEQ, NINP, G, (int)blockIdx.x);
;             pg8::EpiScaleBf16<false> E{PROJ, NINP, SSQ + (2 * l) * SEQ};
;             pg8::gemm_phase<pg8::EpiScaleBf16<false>, pg8::StaticOrder, true, true>(lds, g, S, E);
;             if ((int)blockIdx.x >= (SEQ / 256) * (NINP / 256) - 2 * G) tr_drain(a, lds, tid_, (int*)(ws + WS_CNT) + 24 + 2 * l, l, 1, 1);
;         } else if (sp == 1 && (PHM & 4)) {
;             for (int m = gw; m < SEQ; m += NGW) post_proj_row(a, l, m, lane);
;         } else if (sp == 2 && (PHM & 8)) {
;             if ((int)blockIdx.x < 6) fox_cumsum(a, (int)blockIdx.x, lds);
;             { pg8::Gemm g{PROJ + C_MQ, (const bf16_t*)(ws + WS_WQUP + l * SZ_WQUP), SEQ, NQUPP, 512, NINP}; pg8::StaticOrder S; S.init(SEQ, NQUPP, G, (int)blockIdx.x);
;               pg8::EpiScaleBf16<false> E{QC, NQUPP, nullptr};
;               pg8::gemm_phase<pg8::EpiScaleBf16<false>, pg8::StaticOrder, true, true>(lds, g, S, E); }
;             { pg8::Gemm g{PROJ + C_CKV, (const bf16_t*)(ws + WS_WKVUP + l * SZ_WKVUP), SEQ, NKVUP, 256, NINP}; pg8::StaticOrder S; if (G == 256) S.init(SEQ, NKVUP, 96, (int)blockIdx.x >= 160 ? (int)blockIdx.x - 160 : 192); else S.init(SEQ, NKVUP, G, (int)((blockIdx.x + 128) % G));
;               pg8::EpiScaleBf16<false> E{KVC, NKVUP, nullptr};
;               pg8::gemm_phase<pg8::EpiScaleBf16<false>, pg8::StaticOrder, true, true>(lds, g, S, E); }
;         } else if (sp == 3 && (PHM & 16)) {
;             for (int m = gw; m < SEQ; m += NGW) post_mla_row(a, l, m, lane);
;         } else if (sp == 4 && (PHM & 32)) {
;             attention_phase<0>(a, l, lds, 0);
.LBB0_274:
	s_waitcnt lgkmcnt(0)
	s_lshr_b32 s0, s16, 16
	v_writelane_b32 v254, s0, 7
	s_and_b32 s0, s16, 0xffff
	s_lshl_b32 s2, s82, 3
	s_lshl_b32 s73, s22, 3
	s_cmpk_lt_i32 s82, 0x100
	s_cselect_b64 s[4:5], -1, 0
	s_ashr_i32 s84, s82, 31
	v_writelane_b32 v254, s2, 8
	s_lshr_b32 s2, s84, 29
	s_add_i32 s2, s82, s2
	s_ashr_i32 s6, s2, 3
	s_and_b32 s2, s2, -8
	s_sub_i32 s7, s82, s2
	s_mul_i32 s1, s23, s22
	s_lshl_b32 s2, s7, 5
	s_ashr_i32 s23, s22, 31
	v_writelane_b32 v254, s4, 9
	s_cmpk_lt_i32 s82, 0x400
	v_bfe_u32 v1, v0, 10, 10
	v_writelane_b32 v254, s5, 10
	s_cselect_b64 s[4:5], -1, 0
	v_writelane_b32 v254, s4, 11
	v_bfe_u32 v0, v0, 20, 10
	v_mad_u32_u24 v197, v0, s0, v1
	v_writelane_b32 v254, s5, 12
	s_lshl_b32 s4, s7, 7
	s_lshl_b32 s5, s0, 8
	s_cmp_lt_i32 s82, 6
	v_writelane_b32 v254, s5, 13
	s_cselect_b64 s[8:9], -1, 0
	v_writelane_b32 v254, s8, 14
	s_cmpk_lt_i32 s82, 0xa0
	s_mul_i32 s57, s1, s3
	v_writelane_b32 v254, s9, 15
	s_cselect_b64 s[8:9], -1, 0
	v_writelane_b32 v254, s8, 16
	s_cmpk_lg_i32 s22, 0x100
	v_cvt_f32_u32_e32 v0, s22
	v_writelane_b32 v254, s9, 17
	s_cselect_b64 s[8:9], -1, 0
	v_writelane_b32 v254, s8, 18
	s_add_i32 s5, s82, 0xffffff60
	v_rcp_iflag_f32_e32 v0, v0
	v_writelane_b32 v254, s9, 19
	s_add_i32 s8, s82, 0x80
	s_cmpk_gt_i32 s82, 0x9f
	s_cselect_b32 s5, s5, 0xc0
	s_cmpk_lt_i32 s82, 0x260
	v_writelane_b32 v254, s5, 20
	s_cselect_b64 s[10:11], -1, 0
	s_lshl_b32 s5, s22, 1
	s_sub_i32 s5, 0x260, s5
	v_writelane_b32 v254, s10, 21
	s_cmp_ge_i32 s82, s5
	s_mul_i32 s5, s7, 33
	v_writelane_b32 v254, s11, 22
	s_cselect_b64 s[10:11], -1, 0
	s_cmp_lt_i32 s7, 0
	s_mul_i32 s9, s7, 0x81
	s_cselect_b32 s0, s5, s2
	s_movk_i32 s2, 0x4d
	s_cselect_b32 s1, s9, s4
	s_cselect_b32 s3, 21, 20
	s_cselect_b32 s9, s2, 0x4c
	s_add_i32 s0, s0, s6
	s_ashr_i32 s2, s0, 31
	s_lshr_b32 s2, s2, 28
	s_add_i32 s2, s0, s2
	s_ashr_i32 s4, s2, 4
	s_and_b32 s2, s2, 0xfff0
	s_sub_i32 s2, s0, s2
	s_bfe_u32 s0, s2, 0x10007
	s_add_i32 s5, s2, s0
	s_bfe_i32 s0, s5, 0x80000
	s_and_b32 s5, s5, 0xfe
	v_writelane_b32 v254, s10, 23
	s_sub_i32 s2, s2, s5
	s_lshl_b32 s4, s4, 1
	v_writelane_b32 v254, s11, 24
	s_sext_i32_i16 s10, s0
	s_sext_i32_i8 s2, s2
	s_add_i32 s12, s4, s2
	s_ashr_i32 s2, s10, 1
	s_add_i32 s1, s1, s6
	v_writelane_b32 v254, s2, 25
	s_ashr_i32 s2, s1, 31
	s_lshr_b32 s2, s2, 25
	s_add_i32 s2, s1, s2
	s_ashr_i32 s4, s2, 7
	s_and_b32 s2, s2, 0xff80
	s_sub_i32 s1, s1, s2
	s_bfe_u32 s2, s1, 0x10007
	s_add_i32 s5, s1, s2
	s_bfe_i32 s2, s5, 0x80000
	s_and_b32 s5, s5, 0xfc
	s_sub_i32 s1, s1, s5
	s_lshr_b32 s0, s10, 1
	s_lshl_b32 s4, s4, 2
	s_sext_i32_i16 s10, s2
	s_sext_i32_i8 s1, s1
	s_mul_i32 s3, s7, s3
	s_add_i32 s14, s4, s1
	s_ashr_i32 s1, s10, 2
	s_add_i32 s3, s3, s6
	v_writelane_b32 v254, s1, 26
	s_mul_hi_i32 s1, s3, 0x66666667
	s_lshr_b32 s4, s1, 31
	s_ashr_i32 s1, s1, 2
	s_add_i32 s1, s1, s4
	s_mul_i32 s4, s1, 10
	s_sub_i32 s3, s3, s4
	s_bfe_u32 s4, s3, 0x10007
	s_add_i32 s5, s3, s4
	s_bfe_i32 s4, s5, 0x80000
	s_and_b32 s5, s5, 0xfe
	s_sub_i32 s3, s3, s5
	s_lshl_b32 s1, s1, 1
	s_sext_i32_i8 s3, s3
	s_lshr_b32 s2, s10, 2
	s_sext_i32_i16 s10, s4
	s_add_i32 s1, s1, s3
	s_lshr_b32 s4, s10, 1
	v_writelane_b32 v254, s1, 27
	s_ashr_i32 s1, s10, 1
	v_writelane_b32 v254, s1, 28
	s_bfe_i64 s[4:5], s[4:5], 0x100000
	s_mul_i32 s1, s7, s9
	s_lshl_b64 s[4:5], s[4:5], 18
	s_add_i32 s1, s1, s6
	v_writelane_b32 v254, s4, 29
	s_mul_hi_i32 s3, s1, 0x6bca1af3
	s_ashr_i32 s13, s12, 31
	v_writelane_b32 v254, s5, 30
	s_lshr_b32 s4, s3, 31
	s_ashr_i32 s3, s3, 4
	s_add_i32 s3, s3, s4
	s_lshr_b32 s3, s3, 1
	s_lshl_b32 s5, s3, 2
	s_mul_i32 s3, s3, 0x4c
	s_sub_i32 s1, s1, s3
	s_bfe_u32 s3, s1, 0x10007
	s_add_i32 s3, s1, s3
	s_bfe_i32 s4, s3, 0x80000
	s_and_b32 s3, s3, 0xfc
	s_sub_i32 s1, s1, s3
	s_sext_i32_i16 s6, s4
;     __host__ __device__ bool next(int i, Unit& u) const {
;         const long L = (long)i * G + c; if (L >= nwg) return false;
;         int wgid = (int)L; { const int q = nwg / NXCD, r = nwg % NXCD, xcd = wgid % NXCD, off = wgid / NXCD; wgid = (xcd < r ? xcd * (q + 1) : r * (q + 1) + (xcd - r) * q) + off; }
;         const int nig = WGM * nN, gid = wgid / nig, fm = gid * WGM, gsz = (nM - fm) < WGM ? (nM - fm) : WGM;
;         u.pm = fm + ((wgid % nig) % gsz); u.pn = (wgid % nig) / gsz; return true;
;     }
; __global__ void __launch_bounds__(512, 2) fwd_kernel(Args a_unused) {
;     ...
;         if (sp == 0 && (PHM & 2)) {
;             pg8::Gemm g{XB, (const bf16_t*)(ws + WS_WIN + l * SZ_WIN), SEQ, NINP, DM, DM}; pg8::StaticOrder S; S.init(SEQ, NINP, G, (int)blockIdx.x);
;             pg8::EpiScaleBf16<false> E{PROJ, NINP, SSQ + (2 * l) * SEQ};
;             pg8::gemm_phase<pg8::EpiScaleBf16<false>, pg8::StaticOrder, true, true>(lds, g, S, E);
;             if ((int)blockIdx.x >= (SEQ / 256) * (NINP / 256) - 2 * G) tr_drain(a, lds, tid_, (int*)(ws + WS_CNT) + 24 + 2 * l, l, 1, 1);
;         } else if (sp == 1 && (PHM & 4)) {
;             for (int m = gw; m < SEQ; m += NGW) post_proj_row(a, l, m, lane);
;         } else if (sp == 2 && (PHM & 8)) {
;             if ((int)blockIdx.x < 6) fox_cumsum(a, (int)blockIdx.x, lds);
;             { pg8::Gemm g{PROJ + C_MQ, (const bf16_t*)(ws + WS_WQUP + l * SZ_WQUP), SEQ, NQUPP, 512, NINP}; pg8::StaticOrder S; S.init(SEQ, NQUPP, G, (int)blockIdx.x);
;               pg8::EpiScaleBf16<false> E{QC, NQUPP, nullptr};
;               pg8::gemm_phase<pg8::EpiScaleBf16<false>, pg8::StaticOrder, true, true>(lds, g, S, E); }
;             { pg8::Gemm g{PROJ + C_CKV, (const bf16_t*)(ws + WS_WKVUP + l * SZ_WKVUP), SEQ, NKVUP, 256, NINP}; pg8::StaticOrder S; if (G == 256) S.init(SEQ, NKVUP, 96, (int)blockIdx.x >= 160 ? (int)blockIdx.x - 160 : 192); else S.init(SEQ, NKVUP, G, (int)((blockIdx.x + 128) % G));
;               pg8::EpiScaleBf16<false> E{KVC, NKVUP, nullptr};
;               pg8::gemm_phase<pg8::EpiScaleBf16<false>, pg8::StaticOrder, true, true>(lds, g, S, E); }
;         } else if (sp == 3 && (PHM & 16)) {
;             for (int m = gw; m < SEQ; m += NGW) post_mla_row(a, l, m, lane);
;         } else if (sp == 4 && (PHM & 32)) {
;             attention_phase<0>(a, l, lds, 0);
	s_sext_i32_i8 s1, s1
	s_add_i32 s10, s5, s1
	s_ashr_i32 s1, s6, 2
	s_lshr_b32 s4, s6, 2
	v_writelane_b32 v254, s1, 31
	s_lshl_b64 s[6:7], s[12:13], 22
	v_writelane_b32 v254, s6, 32
	s_bfe_i64 s[0:1], s[0:1], 0x100000
	s_ashr_i32 s15, s14, 31
	v_writelane_b32 v254, s7, 33
	s_lshl_b64 s[6:7], s[0:1], 22
	v_writelane_b32 v254, s6, 34
	s_bfe_i64 s[2:3], s[2:3], 0x100000
	s_lshl_b64 s[2:3], s[2:3], 20
	v_writelane_b32 v254, s7, 35
	s_mov_b32 s6, s14
	v_writelane_b32 v254, s6, 36
	s_lshl_b64 s[0:1], s[0:1], 20
	s_ashr_i32 s11, s10, 31
	v_writelane_b32 v254, s7, 37
	s_lshl_b64 s[6:7], s[14:15], 20
	v_writelane_b32 v254, s6, 38
	v_mul_f32_e32 v0, 0x4f7ffffe, v0
	v_cvt_u32_f32_e32 v0, v0
	v_writelane_b32 v254, s7, 39
	v_writelane_b32 v254, s2, 40
	s_movk_i32 s89, 0xc00
	s_movk_i32 s81, 0x2600
	v_writelane_b32 v254, s3, 41
	s_mov_b32 s2, s12
	v_writelane_b32 v254, s2, 42
	s_mov_b32 s17, 0x10000
	v_mov_b32_e32 v1, 0
	v_writelane_b32 v254, s3, 43
	s_lshl_b64 s[2:3], s[12:13], 20
	v_writelane_b32 v254, s2, 44
	s_mov_b32 s24, 0x14000
	s_movk_i32 s86, 0x4000
	v_writelane_b32 v254, s3, 45
	v_writelane_b32 v254, s0, 46
	s_movk_i32 s3, 0xa00
	s_movk_i32 s93, 0x60
	v_writelane_b32 v254, s1, 47
	s_mov_b32 s0, s10
	v_writelane_b32 v254, s0, 48
	s_mov_b32 s87, 0x18000
	s_mov_b32 s74, 0x8000
	v_writelane_b32 v254, s1, 49
	s_lshl_b64 s[0:1], s[10:11], 20
	v_writelane_b32 v254, s0, 50
	s_mov_b32 s69, 0x1c000
	s_mov_b32 s78, 0xc000
	v_writelane_b32 v254, s1, 51
	s_bfe_i64 s[0:1], s[4:5], 0x100000
	s_lshl_b64 s[0:1], s[0:1], 20
	v_writelane_b32 v254, s0, 52
	v_mov_b32_e32 v198, 0x358637bd
	s_mov_b32 s16, 0x800000
	v_writelane_b32 v254, s1, 53
	s_sub_i32 s0, 0, s22
	v_readfirstlane_b32 s1, v0
	s_mul_i32 s0, s0, s1
	s_mul_hi_u32 s0, s1, s0
	s_add_i32 s1, s1, s0
	s_mul_hi_u32 s0, s8, s1
	s_mul_i32 s0, s0, s22
	s_sub_i32 s0, s8, s0
	s_sub_i32 s1, s0, s22
	s_cmp_ge_u32 s0, s22
	s_cselect_b32 s0, s1, s0
	s_sub_i32 s1, s0, s22
	s_cmp_ge_u32 s0, s22
	s_cselect_b32 s0, s1, s0
	v_writelane_b32 v254, s0, 54
	s_mul_i32 s0, s22, 0x6000
	s_mul_hi_i32 s1, s73, 0xc00
	v_writelane_b32 v254, s0, 55
	v_mov_b32_e32 v199, 0x2000
	v_mbcnt_lo_u32_b32 v0, -1, 0
	v_writelane_b32 v254, s1, 56
	s_mul_i32 s0, s22, 0x5000
	s_mul_hi_i32 s1, s73, 0xa00
	v_writelane_b32 v254, s0, 57
	v_mov_b32_e32 v216, 1
	v_mov_b64_e32 v[200:201], 0x100
	v_writelane_b32 v254, s1, 58
	s_lshl_b32 s0, s82, 8
	v_writelane_b32 v254, s0, 59
	s_lshl_b32 s0, s22, 8
	v_writelane_b32 v254, s0, 60
	s_mul_i32 s0, s22, 0x13000
	v_writelane_b32 v254, s0, 61
	s_lshl_b32 s0, s82, 6
	v_writelane_b32 v254, s0, 62
	s_lshl_b32 s0, s22, 6
	v_writelane_b32 v254, s0, 63
	s_mov_b32 s0, 0x20fc0
	s_add_i32 s88, s0, 0x100
	s_mov_b32 s0, 0x20080
	s_addk_i32 s0, 0x100
	v_writelane_b32 v255, s0, 0
	s_mov_b32 s0, 0x20084
	s_addk_i32 s0, 0x100
	v_writelane_b32 v255, s0, 1
	v_writelane_b32 v255, s73, 2
	v_writelane_b32 v255, s84, 3
	v_mov_b64_e32 v[202:203], 0xff
	v_mbcnt_hi_u32_b32 v217, -1, v0
	v_mov_b32_e32 v218, 0x7f800000
	v_mov_b32_e32 v219, 0xff800000
	v_mov_b32_e32 v220, 0x840
	v_mov_b32_e32 v221, 0x1080
	v_mov_b32_e32 v253, 0x100
	v_bfrev_b32_e32 v226, 40
	v_mov_b32_e32 v204, 0x3f317218
	v_mov_b64_e32 v[206:207], 0x260
	v_mov_b64_e32 v[208:209], 0x25f
	s_mov_b32 s79, 0x2aaaaaab
	s_mov_b32 s75, 0x41000000
	s_mov_b32 s83, 0x30000
	s_mov_b32 s68, 0x60000
	s_mov_b32 s70, 0x20000
	s_mov_b32 s72, 0x24000
	s_mov_b32 s60, 0x2c000
	s_mov_b32 s91, 0x6c000
	s_mov_b32 s56, 0x70000
	s_movk_i32 s71, 0x1246
	s_movk_i32 s54, 0x4918
	s_movk_i32 s25, 0xf05
	s_movk_i32 s55, 0xeff
	s_mov_b64 s[94:95], 0x80
	s_mov_b64 s[96:97], 0x100
	s_mov_b32 s80, 0x3dd53b94
	s_mov_b32 s92, 0x3e0293ee
	s_mov_b32 s90, 0x3e38aa3b
	s_mov_b32 s34, 0x3b000000
	s_mov_b32 s37, 0
	v_writelane_b32 v255, s57, 4
	s_branch .LBB0_278

;     __host__ __device__ bool next(int i, Unit& u) const {
;         const long L = (long)i * G + c; if (L >= nwg) return false;
;         int wgid = (int)L; { const int q = nwg / NXCD, r = nwg % NXCD, xcd = wgid % NXCD, off = wgid / NXCD; wgid = (xcd < r ? xcd * (q + 1) : r * (q + 1) + (xcd - r) * q) + off; }
;         const int nig = WGM * nN, gid = wgid / nig, fm = gid * WGM, gsz = (nM - fm) < WGM ? (nM - fm) : WGM;
;         u.pm = fm + ((wgid % nig) % gsz); u.pn = (wgid % nig) / gsz; return true;
;     }
; template <class Epi, class Sched, bool ALIGN_EPI = false, bool SP2 = false>
; __device__ __forceinline__ void gemm_phase(PG8_LAS unsigned char* lds, const Gemm g, const Sched& S, const Epi& E) {
;     ...
;         const bool has_next = S.next(ui + 1, nxt);
;         const char* nA = has_next ? (const char*)g.A + (size_t)nxt.pm * tstepA : cA; const char* nB = has_next ? (const char*)g.Bt + (size_t)nxt.pn * tstepB : cB;
.LBB0_1431:
	s_add_i32 s52, s52, 1
	s_mul_i32 s2, s52, s23
	s_mul_hi_u32 s4, s52, s22
	s_add_i32 s4, s4, s2
	s_mul_i32 s2, s52, s22
	s_add_u32 s38, s2, s82
	s_addc_u32 s39, s4, s84
	v_cmp_gt_i64_e32 vcc, s[38:39], v[208:209]
	v_cmp_lt_i64_e64 s[4:5], s[38:39], v[206:207]
	s_cbranch_vccnz .LBB0_1433
	s_ashr_i32 s2, s38, 31
	s_lshr_b32 s2, s2, 29
	s_add_i32 s2, s38, s2
	s_ashr_i32 s26, s2, 3
	s_and_b32 s2, s2, -8
	s_sub_i32 s2, s38, s2
	s_cmp_lt_i32 s2, 0
	s_movk_i32 s27, 0x4d
	s_cselect_b32 s27, s27, 0x4c
	s_mul_i32 s2, s2, s27
	s_add_i32 s2, s2, s26
	s_mul_hi_i32 s26, s2, 0x6bca1af3
	s_lshr_b32 s27, s26, 31
	s_ashr_i32 s26, s26, 4
	s_add_i32 s26, s26, s27
	s_lshr_b32 s26, s26, 1
	s_lshl_b32 s27, s26, 2
	s_sub_i32 s33, 32, s27
	s_min_i32 s33, s33, 4
	s_abs_i32 s34, s33
	v_cvt_f32_u32_e32 v2, s34
	s_sub_i32 s38, 0, s34
	s_mul_i32 s26, s26, 0x4c
	s_sub_i32 s2, s2, s26
	v_rcp_iflag_f32_e32 v2, v2
	s_abs_i32 s26, s2
	s_xor_b32 s35, s2, s33
	s_ashr_i32 s35, s35, 31
	v_mul_f32_e32 v2, 0x4f7ffffe, v2
	v_cvt_u32_f32_e32 v2, v2
	s_nop 0
	v_readfirstlane_b32 s39, v2
	s_mul_i32 s38, s38, s39
	s_mul_hi_u32 s38, s39, s38
	s_add_i32 s39, s39, s38
	s_mul_hi_u32 s38, s26, s39
	s_mul_i32 s39, s38, s34
	s_sub_i32 s26, s26, s39
	s_add_i32 s40, s38, 1
	s_sub_i32 s39, s26, s34
	s_cmp_ge_u32 s26, s34
	s_cselect_b32 s38, s40, s38
	s_cselect_b32 s26, s39, s26
	s_add_i32 s39, s38, 1
	s_cmp_ge_u32 s26, s34
	s_cselect_b32 s26, s39, s38
	s_xor_b32 s26, s26, s35
	s_sub_i32 s26, s26, s35
	s_mul_i32 s33, s26, s33
	s_sub_i32 s2, s2, s33
	s_add_i32 s34, s27, s2
